# MO8+TRIM + IL (SP2 load segments: LDS reads interleaved with LDS-DMA loads) + Z0b (no accumulator zeroing, srcC=0 copies in the first K-iteration)
# speedup vs baseline: 1.0052x; 1.0052x over previous
.Lz0_0_0_ret:
	s_add_i32 s49, s49, s26
	v_lshl_add_u64 v[172:173], s[22:23], 0, v[0:1]
	s_mov_b32 m0, s49
	s_nop 0
	global_load_lds_dwordx4 v[172:173], off
	ds_read_b128 v[194:197], v147 offset:16384
	ds_read_b128 v[198:201], v147 offset:17408
	s_add_i32 m0, s49, 0x2000
	s_add_u32 s50, s22, 0x100000
	v_lshl_add_u64 v[178:179], s[22:23], 0, v[130:131]
	s_addc_u32 s51, s23, 0
	s_add_i32 s49, s52, s26
	global_load_lds_dwordx4 v[178:179], off
	ds_read_b128 v[202:205], v147 offset:18432
	ds_read_b128 v[206:209], v147 offset:19456
	v_lshl_add_u64 v[180:181], s[50:51], 0, v[0:1]
	s_mov_b32 m0, s49
	v_lshl_add_u64 v[210:211], s[24:25], 0, v[132:133]
	global_load_lds_dwordx4 v[180:181], off
	ds_read_b128 v[228:231], v147 offset:20480
	ds_read_b128 v[232:235], v147 offset:21504
	v_lshl_add_u64 v[180:181], s[50:51], 0, v[130:131]
	s_add_i32 m0, s49, 0x2000
	s_nop 0
	global_load_lds_dwordx4 v[180:181], off
	ds_read_b128 v[236:239], v147 offset:22528
	ds_read_b128 v[240:243], v147 offset:23552
	v_lshl_add_u64 v[180:181], s[24:25], 0, v[134:135]
	s_mov_b32 m0, s31
	s_nop 0
	global_load_lds_dwordx4 v[180:181], off
	s_mov_b32 m0, s36
	s_nop 0
	global_load_lds_dwordx4 v[210:211], off
	s_cmp_eq_u32 s48, -2
	s_cbranch_scc1 .Lz0_0_1
	s_waitcnt vmcnt(8)
	s_waitcnt lgkmcnt(0)
	s_setprio 1
	s_barrier
	v_mfma_f32_16x16x32_bf16 v[62:65], v[140:143], v[194:197], v[62:65]
	v_mfma_f32_16x16x32_bf16 v[62:65], v[148:151], v[198:201], v[62:65]
	v_mfma_f32_16x16x32_bf16 v[54:57], v[148:151], v[206:209], v[54:57]
	v_mfma_f32_16x16x32_bf16 v[54:57], v[140:143], v[202:205], v[54:57]
	v_mfma_f32_16x16x32_bf16 v[38:41], v[140:143], v[228:231], v[38:41]
	v_mfma_f32_16x16x32_bf16 v[38:41], v[148:151], v[232:235], v[38:41]
	v_mfma_f32_16x16x32_bf16 v[22:25], v[148:151], v[240:243], v[22:25]
	v_mfma_f32_16x16x32_bf16 v[22:25], v[140:143], v[236:239], v[22:25]
	v_mfma_f32_16x16x32_bf16 v[14:17], v[152:155], v[236:239], v[14:17]
	v_mfma_f32_16x16x32_bf16 v[14:17], v[156:159], v[240:243], v[14:17]
	v_mfma_f32_16x16x32_bf16 v[30:33], v[156:159], v[232:235], v[30:33]
	v_mfma_f32_16x16x32_bf16 v[30:33], v[152:155], v[228:231], v[30:33]
	v_mfma_f32_16x16x32_bf16 v[46:49], v[152:155], v[202:205], v[46:49]
	v_mfma_f32_16x16x32_bf16 v[46:49], v[156:159], v[206:209], v[46:49]
	v_mfma_f32_16x16x32_bf16 v[58:61], v[156:159], v[198:201], v[58:61]
	v_mfma_f32_16x16x32_bf16 v[58:61], v[152:155], v[194:197], v[58:61]
	v_mfma_f32_16x16x32_bf16 v[50:53], v[160:163], v[194:197], v[50:53]
	v_mfma_f32_16x16x32_bf16 v[50:53], v[164:167], v[198:201], v[50:53]
	v_mfma_f32_16x16x32_bf16 v[34:37], v[164:167], v[206:209], v[34:37]
	v_mfma_f32_16x16x32_bf16 v[34:37], v[160:163], v[202:205], v[34:37]
	v_mfma_f32_16x16x32_bf16 v[18:21], v[160:163], v[228:231], v[18:21]
	v_mfma_f32_16x16x32_bf16 v[18:21], v[164:167], v[232:235], v[18:21]
	v_mfma_f32_16x16x32_bf16 v[6:9], v[164:167], v[240:243], v[6:9]
	v_mfma_f32_16x16x32_bf16 v[6:9], v[160:163], v[236:239], v[6:9]
	v_mfma_f32_16x16x32_bf16 v[2:5], v[168:171], v[236:239], v[2:5]
	v_mfma_f32_16x16x32_bf16 v[2:5], v[190:193], v[240:243], v[2:5]
	v_mfma_f32_16x16x32_bf16 v[10:13], v[190:193], v[232:235], v[10:13]
	v_mfma_f32_16x16x32_bf16 v[10:13], v[168:171], v[228:231], v[10:13]
	v_mfma_f32_16x16x32_bf16 v[26:29], v[168:171], v[202:205], v[26:29]
	v_mfma_f32_16x16x32_bf16 v[26:29], v[190:193], v[206:209], v[26:29]
	v_mfma_f32_16x16x32_bf16 v[42:45], v[190:193], v[198:201], v[42:45]
	v_mfma_f32_16x16x32_bf16 v[42:45], v[168:171], v[194:197], v[42:45]
	s_barrier
	s_setprio 0
.Lz0_0_1_ret:
	s_add_i32 s49, 0, 0x18000
	s_add_i32 s50, 0, 0x1c000
	v_add_u32_e32 v156, s49, v145
	v_add_u32_e32 v175, s50, v145
	ds_read_b128 v[140:143], v156
	ds_read_b128 v[148:151], v156 offset:1024
	ds_read_b128 v[152:155], v156 offset:2048
	ds_read_b128 v[156:159], v156 offset:3072
	ds_read_b128 v[160:163], v175
	ds_read_b128 v[164:167], v175 offset:1024
	ds_read_b128 v[168:171], v175 offset:2048
	ds_read_b128 v[190:193], v175 offset:3072
	s_add_u32 s24, s24, 0x100000
	s_addc_u32 s25, s25, 0
	s_mov_b32 m0, s37
	v_lshl_add_u64 v[244:245], s[24:25], 0, v[134:135]
	ds_read_b128 v[194:197], v147 offset:32768
	ds_read_b128 v[198:201], v147 offset:33792
	ds_read_b128 v[202:205], v147 offset:34816
	ds_read_b128 v[206:209], v147 offset:35840
	ds_read_b128 v[228:231], v147 offset:36864
	ds_read_b128 v[232:235], v147 offset:37888
	ds_read_b128 v[236:239], v147 offset:38912
	ds_read_b128 v[240:243], v147 offset:39936
	global_load_lds_dwordx4 v[244:245], off
	v_lshl_add_u64 v[244:245], s[24:25], 0, v[132:133]
	s_mov_b32 m0, s38
	s_nop 0
	global_load_lds_dwordx4 v[244:245], off
	s_waitcnt vmcnt(8)
	s_waitcnt lgkmcnt(0)
	s_setprio 1
	s_barrier
	v_mfma_f32_16x16x32_bf16 v[126:129], v[140:143], v[194:197], v[126:129]
	v_mfma_f32_16x16x32_bf16 v[126:129], v[148:151], v[198:201], v[126:129]
	v_mfma_f32_16x16x32_bf16 v[118:121], v[148:151], v[206:209], v[118:121]
	v_mfma_f32_16x16x32_bf16 v[118:121], v[140:143], v[202:205], v[118:121]
	v_mfma_f32_16x16x32_bf16 v[102:105], v[140:143], v[228:231], v[102:105]
	v_mfma_f32_16x16x32_bf16 v[102:105], v[148:151], v[232:235], v[102:105]
	v_mfma_f32_16x16x32_bf16 v[86:89], v[148:151], v[240:243], v[86:89]
	v_mfma_f32_16x16x32_bf16 v[86:89], v[140:143], v[236:239], v[86:89]
	v_mfma_f32_16x16x32_bf16 v[78:81], v[152:155], v[236:239], v[78:81]
	v_mfma_f32_16x16x32_bf16 v[78:81], v[156:159], v[240:243], v[78:81]
	v_mfma_f32_16x16x32_bf16 v[94:97], v[156:159], v[232:235], v[94:97]
	v_mfma_f32_16x16x32_bf16 v[94:97], v[152:155], v[228:231], v[94:97]
	v_mfma_f32_16x16x32_bf16 v[110:113], v[152:155], v[202:205], v[110:113]
	v_mfma_f32_16x16x32_bf16 v[110:113], v[156:159], v[206:209], v[110:113]
	v_mfma_f32_16x16x32_bf16 v[122:125], v[156:159], v[198:201], v[122:125]
	v_mfma_f32_16x16x32_bf16 v[122:125], v[152:155], v[194:197], v[122:125]
	v_mfma_f32_16x16x32_bf16 v[114:117], v[160:163], v[194:197], v[114:117]
	v_mfma_f32_16x16x32_bf16 v[114:117], v[164:167], v[198:201], v[114:117]
	v_mfma_f32_16x16x32_bf16 v[98:101], v[164:167], v[206:209], v[98:101]
	v_mfma_f32_16x16x32_bf16 v[98:101], v[160:163], v[202:205], v[98:101]
	v_mfma_f32_16x16x32_bf16 v[82:85], v[160:163], v[228:231], v[82:85]
	v_mfma_f32_16x16x32_bf16 v[82:85], v[164:167], v[232:235], v[82:85]
	v_mfma_f32_16x16x32_bf16 v[70:73], v[164:167], v[240:243], v[70:73]
	v_mfma_f32_16x16x32_bf16 v[70:73], v[160:163], v[236:239], v[70:73]
	v_mfma_f32_16x16x32_bf16 v[66:69], v[168:171], v[236:239], v[66:69]
	v_mfma_f32_16x16x32_bf16 v[66:69], v[190:193], v[240:243], v[66:69]
	v_mfma_f32_16x16x32_bf16 v[74:77], v[190:193], v[232:235], v[74:77]
	v_mfma_f32_16x16x32_bf16 v[74:77], v[168:171], v[228:231], v[74:77]
	v_mfma_f32_16x16x32_bf16 v[90:93], v[168:171], v[202:205], v[90:93]
	v_mfma_f32_16x16x32_bf16 v[90:93], v[190:193], v[206:209], v[90:93]
	v_mfma_f32_16x16x32_bf16 v[106:109], v[190:193], v[198:201], v[106:109]
	v_mfma_f32_16x16x32_bf16 v[106:109], v[168:171], v[194:197], v[106:109]
	s_barrier
	s_setprio 0
	s_add_i32 s24, s49, s26
	v_lshl_add_u64 v[172:173], v[172:173], 0, s[34:35]
	s_mov_b32 m0, s24
	s_nop 0
	global_load_lds_dwordx4 v[172:173], off
	ds_read_b128 v[194:197], v147 offset:49152
	ds_read_b128 v[198:201], v147 offset:50176
	s_add_i32 m0, s24, 0x2000
	s_add_u32 s22, s22, 0x100080
	v_lshl_add_u64 v[172:173], v[178:179], 0, s[34:35]
	s_addc_u32 s23, s23, 0
	s_add_i32 s24, s50, s26
	global_load_lds_dwordx4 v[172:173], off
	ds_read_b128 v[202:205], v147 offset:51200
	ds_read_b128 v[206:209], v147 offset:52224
	v_lshl_add_u64 v[172:173], s[22:23], 0, v[0:1]
	s_mov_b32 m0, s24
	s_nop 0
	global_load_lds_dwordx4 v[172:173], off
	ds_read_b128 v[228:231], v147 offset:53248
	ds_read_b128 v[232:235], v147 offset:54272
	v_lshl_add_u64 v[172:173], s[22:23], 0, v[130:131]
	s_add_i32 m0, s24, 0x2000
	s_nop 0
	global_load_lds_dwordx4 v[172:173], off
	ds_read_b128 v[236:239], v147 offset:55296
	ds_read_b128 v[240:243], v147 offset:56320
	v_lshl_add_u64 v[172:173], v[180:181], 0, s[34:35]
	s_mov_b32 m0, s39
	s_nop 0
	global_load_lds_dwordx4 v[172:173], off
	v_lshl_add_u64 v[172:173], v[210:211], 0, s[34:35]
	s_mov_b32 m0, s40
	s_nop 0
	global_load_lds_dwordx4 v[172:173], off
	s_waitcnt vmcnt(8)
	s_waitcnt lgkmcnt(0)
	s_setprio 1
	s_barrier
	v_mfma_f32_16x16x32_bf16 v[62:65], v[140:143], v[194:197], v[62:65]
	v_mfma_f32_16x16x32_bf16 v[62:65], v[148:151], v[198:201], v[62:65]
	v_mfma_f32_16x16x32_bf16 v[54:57], v[148:151], v[206:209], v[54:57]
	v_mfma_f32_16x16x32_bf16 v[54:57], v[140:143], v[202:205], v[54:57]
	v_mfma_f32_16x16x32_bf16 v[38:41], v[140:143], v[228:231], v[38:41]
	v_mfma_f32_16x16x32_bf16 v[38:41], v[148:151], v[232:235], v[38:41]
	v_mfma_f32_16x16x32_bf16 v[22:25], v[148:151], v[240:243], v[22:25]
	v_mfma_f32_16x16x32_bf16 v[22:25], v[140:143], v[236:239], v[22:25]
	v_mfma_f32_16x16x32_bf16 v[14:17], v[152:155], v[236:239], v[14:17]
	v_mfma_f32_16x16x32_bf16 v[14:17], v[156:159], v[240:243], v[14:17]
	v_mfma_f32_16x16x32_bf16 v[30:33], v[156:159], v[232:235], v[30:33]
	v_mfma_f32_16x16x32_bf16 v[30:33], v[152:155], v[228:231], v[30:33]
	v_mfma_f32_16x16x32_bf16 v[46:49], v[152:155], v[202:205], v[46:49]
	v_mfma_f32_16x16x32_bf16 v[46:49], v[156:159], v[206:209], v[46:49]
	v_mfma_f32_16x16x32_bf16 v[58:61], v[156:159], v[198:201], v[58:61]
	v_mfma_f32_16x16x32_bf16 v[58:61], v[152:155], v[194:197], v[58:61]
	v_mfma_f32_16x16x32_bf16 v[50:53], v[160:163], v[194:197], v[50:53]
	v_mfma_f32_16x16x32_bf16 v[50:53], v[164:167], v[198:201], v[50:53]
	v_mfma_f32_16x16x32_bf16 v[34:37], v[164:167], v[206:209], v[34:37]
	v_mfma_f32_16x16x32_bf16 v[34:37], v[160:163], v[202:205], v[34:37]
	v_mfma_f32_16x16x32_bf16 v[18:21], v[160:163], v[228:231], v[18:21]
	v_mfma_f32_16x16x32_bf16 v[18:21], v[164:167], v[232:235], v[18:21]
	v_mfma_f32_16x16x32_bf16 v[6:9], v[164:167], v[240:243], v[6:9]
	v_mfma_f32_16x16x32_bf16 v[6:9], v[160:163], v[236:239], v[6:9]
	v_mfma_f32_16x16x32_bf16 v[2:5], v[168:171], v[236:239], v[2:5]
	v_mfma_f32_16x16x32_bf16 v[2:5], v[190:193], v[240:243], v[2:5]
	v_mfma_f32_16x16x32_bf16 v[10:13], v[190:193], v[232:235], v[10:13]
	v_mfma_f32_16x16x32_bf16 v[10:13], v[168:171], v[228:231], v[10:13]
	v_mfma_f32_16x16x32_bf16 v[26:29], v[168:171], v[202:205], v[26:29]
	v_mfma_f32_16x16x32_bf16 v[26:29], v[190:193], v[206:209], v[26:29]
	v_mfma_f32_16x16x32_bf16 v[42:45], v[190:193], v[198:201], v[42:45]
	v_mfma_f32_16x16x32_bf16 v[42:45], v[168:171], v[194:197], v[42:45]
	s_barrier
	s_setprio 0
	s_add_i32 s48, s48, 2
	s_add_u32 s18, s18, 0x100
	s_addc_u32 s19, s19, 0
	s_add_u32 s46, s46, 0x100
	s_addc_u32 s47, s47, 0
	s_cmp_gt_u32 s48, 61
	s_cbranch_scc0 .LBB0_139
	s_and_b64 vcc, exec, s[4:5]
	s_cbranch_vccz .LBB0_142
	s_barrier

.Lz0_1_0_ret:
	s_add_i32 s53, s53, s38
	v_lshl_add_u64 v[140:141], s[22:23], 0, v[0:1]
	s_mov_b32 m0, s53
	s_nop 0
	global_load_lds_dwordx4 v[140:141], off
	ds_read_b128 v[190:193], v145 offset:16384
	ds_read_b128 v[194:197], v145 offset:17408
	s_add_i32 m0, s53, 0x2000
	s_add_u32 s54, s22, 0x100000
	v_lshl_add_u64 v[186:187], s[22:23], 0, v[130:131]
	s_addc_u32 s55, s23, 0
	s_add_i32 s53, s56, s38
	global_load_lds_dwordx4 v[186:187], off
	ds_read_b128 v[198:201], v145 offset:18432
	ds_read_b128 v[202:205], v145 offset:19456
	v_lshl_add_u64 v[188:189], s[54:55], 0, v[0:1]
	s_mov_b32 m0, s53
	v_lshl_add_u64 v[210:211], s[24:25], 0, v[132:133]
	global_load_lds_dwordx4 v[188:189], off
	ds_read_b128 v[206:209], v145 offset:20480
	ds_read_b128 v[228:231], v145 offset:21504
	v_lshl_add_u64 v[188:189], s[54:55], 0, v[130:131]
	s_add_i32 m0, s53, 0x2000
	s_nop 0
	global_load_lds_dwordx4 v[188:189], off
	ds_read_b128 v[232:235], v145 offset:22528
	ds_read_b128 v[236:239], v145 offset:23552
	v_lshl_add_u64 v[188:189], s[24:25], 0, v[134:135]
	s_mov_b32 m0, s39
	s_nop 0
	global_load_lds_dwordx4 v[188:189], off
	s_mov_b32 m0, s40
	s_nop 0
	global_load_lds_dwordx4 v[210:211], off
	s_cmp_eq_u32 s52, -2
	s_cbranch_scc1 .Lz0_1_1
	s_waitcnt vmcnt(8)
	s_waitcnt lgkmcnt(0)
	s_setprio 1
	s_barrier
	v_mfma_f32_16x16x32_bf16 v[62:65], v[146:149], v[190:193], v[62:65]
	v_mfma_f32_16x16x32_bf16 v[62:65], v[150:153], v[194:197], v[62:65]
	v_mfma_f32_16x16x32_bf16 v[54:57], v[150:153], v[202:205], v[54:57]
	v_mfma_f32_16x16x32_bf16 v[54:57], v[146:149], v[198:201], v[54:57]
	v_mfma_f32_16x16x32_bf16 v[38:41], v[146:149], v[206:209], v[38:41]
	v_mfma_f32_16x16x32_bf16 v[38:41], v[150:153], v[228:231], v[38:41]
	v_mfma_f32_16x16x32_bf16 v[22:25], v[150:153], v[236:239], v[22:25]
	v_mfma_f32_16x16x32_bf16 v[22:25], v[146:149], v[232:235], v[22:25]
	v_mfma_f32_16x16x32_bf16 v[14:17], v[154:157], v[232:235], v[14:17]
	v_mfma_f32_16x16x32_bf16 v[14:17], v[158:161], v[236:239], v[14:17]
	v_mfma_f32_16x16x32_bf16 v[30:33], v[158:161], v[228:231], v[30:33]
	v_mfma_f32_16x16x32_bf16 v[30:33], v[154:157], v[206:209], v[30:33]
	v_mfma_f32_16x16x32_bf16 v[46:49], v[154:157], v[198:201], v[46:49]
	v_mfma_f32_16x16x32_bf16 v[46:49], v[158:161], v[202:205], v[46:49]
	v_mfma_f32_16x16x32_bf16 v[58:61], v[158:161], v[194:197], v[58:61]
	v_mfma_f32_16x16x32_bf16 v[58:61], v[154:157], v[190:193], v[58:61]
	v_mfma_f32_16x16x32_bf16 v[50:53], v[162:165], v[190:193], v[50:53]
	v_mfma_f32_16x16x32_bf16 v[50:53], v[166:169], v[194:197], v[50:53]
	v_mfma_f32_16x16x32_bf16 v[34:37], v[166:169], v[202:205], v[34:37]
	v_mfma_f32_16x16x32_bf16 v[34:37], v[162:165], v[198:201], v[34:37]
	v_mfma_f32_16x16x32_bf16 v[18:21], v[162:165], v[206:209], v[18:21]
	v_mfma_f32_16x16x32_bf16 v[18:21], v[166:169], v[228:231], v[18:21]
	v_mfma_f32_16x16x32_bf16 v[6:9], v[166:169], v[236:239], v[6:9]
	v_mfma_f32_16x16x32_bf16 v[6:9], v[162:165], v[232:235], v[6:9]
	v_mfma_f32_16x16x32_bf16 v[2:5], v[170:173], v[232:235], v[2:5]
	v_mfma_f32_16x16x32_bf16 v[2:5], v[178:181], v[236:239], v[2:5]
	v_mfma_f32_16x16x32_bf16 v[10:13], v[178:181], v[228:231], v[10:13]
	v_mfma_f32_16x16x32_bf16 v[10:13], v[170:173], v[206:209], v[10:13]
	v_mfma_f32_16x16x32_bf16 v[26:29], v[170:173], v[198:201], v[26:29]
	v_mfma_f32_16x16x32_bf16 v[26:29], v[178:181], v[202:205], v[26:29]
	v_mfma_f32_16x16x32_bf16 v[42:45], v[178:181], v[194:197], v[42:45]
	v_mfma_f32_16x16x32_bf16 v[42:45], v[170:173], v[190:193], v[42:45]
	s_barrier
	s_setprio 0
.Lz0_1_1_ret:
	s_add_i32 s53, 0, 0x18000
	s_add_i32 s54, 0, 0x1c000
	v_add_u32_e32 v158, s53, v143
	v_add_u32_e32 v175, s54, v143
	ds_read_b128 v[146:149], v158
	ds_read_b128 v[150:153], v158 offset:1024
	ds_read_b128 v[154:157], v158 offset:2048
	ds_read_b128 v[158:161], v158 offset:3072
	ds_read_b128 v[162:165], v175
	ds_read_b128 v[166:169], v175 offset:1024
	ds_read_b128 v[170:173], v175 offset:2048
	ds_read_b128 v[178:181], v175 offset:3072
	s_add_u32 s24, s24, 0x100000
	s_addc_u32 s25, s25, 0
	s_mov_b32 m0, s41
	v_lshl_add_u64 v[226:227], s[24:25], 0, v[134:135]
	ds_read_b128 v[190:193], v145 offset:32768
	ds_read_b128 v[194:197], v145 offset:33792
	ds_read_b128 v[198:201], v145 offset:34816
	ds_read_b128 v[202:205], v145 offset:35840
	ds_read_b128 v[206:209], v145 offset:36864
	ds_read_b128 v[228:231], v145 offset:37888
	ds_read_b128 v[232:235], v145 offset:38912
	ds_read_b128 v[236:239], v145 offset:39936
	global_load_lds_dwordx4 v[226:227], off
	v_lshl_add_u64 v[226:227], s[24:25], 0, v[132:133]
	s_mov_b32 m0, s42
	s_nop 0
	global_load_lds_dwordx4 v[226:227], off
	s_waitcnt vmcnt(8)
	s_waitcnt lgkmcnt(0)
	s_setprio 1
	s_barrier
	v_mfma_f32_16x16x32_bf16 v[126:129], v[146:149], v[190:193], v[126:129]
	v_mfma_f32_16x16x32_bf16 v[126:129], v[150:153], v[194:197], v[126:129]
	v_mfma_f32_16x16x32_bf16 v[118:121], v[150:153], v[202:205], v[118:121]
	v_mfma_f32_16x16x32_bf16 v[118:121], v[146:149], v[198:201], v[118:121]
	v_mfma_f32_16x16x32_bf16 v[102:105], v[146:149], v[206:209], v[102:105]
	v_mfma_f32_16x16x32_bf16 v[102:105], v[150:153], v[228:231], v[102:105]
	v_mfma_f32_16x16x32_bf16 v[86:89], v[150:153], v[236:239], v[86:89]
	v_mfma_f32_16x16x32_bf16 v[86:89], v[146:149], v[232:235], v[86:89]
	v_mfma_f32_16x16x32_bf16 v[78:81], v[154:157], v[232:235], v[78:81]
	v_mfma_f32_16x16x32_bf16 v[78:81], v[158:161], v[236:239], v[78:81]
	v_mfma_f32_16x16x32_bf16 v[94:97], v[158:161], v[228:231], v[94:97]
	v_mfma_f32_16x16x32_bf16 v[94:97], v[154:157], v[206:209], v[94:97]
	v_mfma_f32_16x16x32_bf16 v[110:113], v[154:157], v[198:201], v[110:113]
	v_mfma_f32_16x16x32_bf16 v[110:113], v[158:161], v[202:205], v[110:113]
	v_mfma_f32_16x16x32_bf16 v[122:125], v[158:161], v[194:197], v[122:125]
	v_mfma_f32_16x16x32_bf16 v[122:125], v[154:157], v[190:193], v[122:125]
	v_mfma_f32_16x16x32_bf16 v[114:117], v[162:165], v[190:193], v[114:117]
	v_mfma_f32_16x16x32_bf16 v[114:117], v[166:169], v[194:197], v[114:117]
	v_mfma_f32_16x16x32_bf16 v[98:101], v[166:169], v[202:205], v[98:101]
	v_mfma_f32_16x16x32_bf16 v[98:101], v[162:165], v[198:201], v[98:101]
	v_mfma_f32_16x16x32_bf16 v[82:85], v[162:165], v[206:209], v[82:85]
	v_mfma_f32_16x16x32_bf16 v[82:85], v[166:169], v[228:231], v[82:85]
	v_mfma_f32_16x16x32_bf16 v[70:73], v[166:169], v[236:239], v[70:73]
	v_mfma_f32_16x16x32_bf16 v[70:73], v[162:165], v[232:235], v[70:73]
	v_mfma_f32_16x16x32_bf16 v[66:69], v[170:173], v[232:235], v[66:69]
	v_mfma_f32_16x16x32_bf16 v[66:69], v[178:181], v[236:239], v[66:69]
	v_mfma_f32_16x16x32_bf16 v[74:77], v[178:181], v[228:231], v[74:77]
	v_mfma_f32_16x16x32_bf16 v[74:77], v[170:173], v[206:209], v[74:77]
	v_mfma_f32_16x16x32_bf16 v[90:93], v[170:173], v[198:201], v[90:93]
	v_mfma_f32_16x16x32_bf16 v[90:93], v[178:181], v[202:205], v[90:93]
	v_mfma_f32_16x16x32_bf16 v[106:109], v[178:181], v[194:197], v[106:109]
	v_mfma_f32_16x16x32_bf16 v[106:109], v[170:173], v[190:193], v[106:109]
	s_barrier
	s_setprio 0
	s_add_i32 s24, s53, s38
	v_lshl_add_u64 v[140:141], v[140:141], 0, s[34:35]
	s_mov_b32 m0, s24
	s_nop 0
	global_load_lds_dwordx4 v[140:141], off
	ds_read_b128 v[190:193], v145 offset:49152
	ds_read_b128 v[194:197], v145 offset:50176
	s_add_i32 m0, s24, 0x2000
	s_add_u32 s22, s22, 0x100080
	v_lshl_add_u64 v[140:141], v[186:187], 0, s[34:35]
	s_addc_u32 s23, s23, 0
	s_add_i32 s24, s54, s38
	global_load_lds_dwordx4 v[140:141], off
	ds_read_b128 v[198:201], v145 offset:51200
	ds_read_b128 v[202:205], v145 offset:52224
	v_lshl_add_u64 v[140:141], s[22:23], 0, v[0:1]
	s_mov_b32 m0, s24
	s_nop 0
	global_load_lds_dwordx4 v[140:141], off
	ds_read_b128 v[206:209], v145 offset:53248
	ds_read_b128 v[228:231], v145 offset:54272
	v_lshl_add_u64 v[140:141], s[22:23], 0, v[130:131]
	s_add_i32 m0, s24, 0x2000
	s_nop 0
	global_load_lds_dwordx4 v[140:141], off
	ds_read_b128 v[232:235], v145 offset:55296
	ds_read_b128 v[236:239], v145 offset:56320
	v_lshl_add_u64 v[140:141], v[188:189], 0, s[34:35]
	s_mov_b32 m0, s43
	s_nop 0
	global_load_lds_dwordx4 v[140:141], off
	v_lshl_add_u64 v[140:141], v[210:211], 0, s[34:35]
	s_mov_b32 m0, s44
	s_nop 0
	global_load_lds_dwordx4 v[140:141], off
	s_waitcnt vmcnt(8)
	s_waitcnt lgkmcnt(0)
	s_setprio 1
	s_barrier
	v_mfma_f32_16x16x32_bf16 v[62:65], v[146:149], v[190:193], v[62:65]
	v_mfma_f32_16x16x32_bf16 v[62:65], v[150:153], v[194:197], v[62:65]
	v_mfma_f32_16x16x32_bf16 v[54:57], v[150:153], v[202:205], v[54:57]
	v_mfma_f32_16x16x32_bf16 v[54:57], v[146:149], v[198:201], v[54:57]
	v_mfma_f32_16x16x32_bf16 v[38:41], v[146:149], v[206:209], v[38:41]
	v_mfma_f32_16x16x32_bf16 v[38:41], v[150:153], v[228:231], v[38:41]
	v_mfma_f32_16x16x32_bf16 v[22:25], v[150:153], v[236:239], v[22:25]
	v_mfma_f32_16x16x32_bf16 v[22:25], v[146:149], v[232:235], v[22:25]
	v_mfma_f32_16x16x32_bf16 v[14:17], v[154:157], v[232:235], v[14:17]
	v_mfma_f32_16x16x32_bf16 v[14:17], v[158:161], v[236:239], v[14:17]
	v_mfma_f32_16x16x32_bf16 v[30:33], v[158:161], v[228:231], v[30:33]
	v_mfma_f32_16x16x32_bf16 v[30:33], v[154:157], v[206:209], v[30:33]
	v_mfma_f32_16x16x32_bf16 v[46:49], v[154:157], v[198:201], v[46:49]
	v_mfma_f32_16x16x32_bf16 v[46:49], v[158:161], v[202:205], v[46:49]
	v_mfma_f32_16x16x32_bf16 v[58:61], v[158:161], v[194:197], v[58:61]
	v_mfma_f32_16x16x32_bf16 v[58:61], v[154:157], v[190:193], v[58:61]
	v_mfma_f32_16x16x32_bf16 v[50:53], v[162:165], v[190:193], v[50:53]
	v_mfma_f32_16x16x32_bf16 v[50:53], v[166:169], v[194:197], v[50:53]
	v_mfma_f32_16x16x32_bf16 v[34:37], v[166:169], v[202:205], v[34:37]
	v_mfma_f32_16x16x32_bf16 v[34:37], v[162:165], v[198:201], v[34:37]
	v_mfma_f32_16x16x32_bf16 v[18:21], v[162:165], v[206:209], v[18:21]
	v_mfma_f32_16x16x32_bf16 v[18:21], v[166:169], v[228:231], v[18:21]
	v_mfma_f32_16x16x32_bf16 v[6:9], v[166:169], v[236:239], v[6:9]
	v_mfma_f32_16x16x32_bf16 v[6:9], v[162:165], v[232:235], v[6:9]
	v_mfma_f32_16x16x32_bf16 v[2:5], v[170:173], v[232:235], v[2:5]
	v_mfma_f32_16x16x32_bf16 v[2:5], v[178:181], v[236:239], v[2:5]
	v_mfma_f32_16x16x32_bf16 v[10:13], v[178:181], v[228:231], v[10:13]
	v_mfma_f32_16x16x32_bf16 v[10:13], v[170:173], v[206:209], v[10:13]
	v_mfma_f32_16x16x32_bf16 v[26:29], v[170:173], v[198:201], v[26:29]
	v_mfma_f32_16x16x32_bf16 v[26:29], v[178:181], v[202:205], v[26:29]
	v_mfma_f32_16x16x32_bf16 v[42:45], v[178:181], v[194:197], v[42:45]
	v_mfma_f32_16x16x32_bf16 v[42:45], v[170:173], v[190:193], v[42:45]
	s_barrier
	s_setprio 0
	s_add_i32 s52, s52, 2
	s_add_u32 s18, s18, 0x100
	s_addc_u32 s19, s19, 0
	s_add_u32 s50, s50, 0x100
	s_addc_u32 s51, s51, 0
	s_cmp_gt_u32 s52, 61
	s_cbranch_scc0 .LBB0_575
	s_and_b64 vcc, exec, s[4:5]
	s_cbranch_vccz .LBB0_578
	s_barrier

.Lz0_2_0_ret:
	s_add_i32 s53, s53, s26
	v_lshl_add_u64 v[140:141], s[18:19], 0, v[0:1]
	s_mov_b32 m0, s53
	s_nop 0
	global_load_lds_dwordx4 v[140:141], off
	ds_read_b128 v[190:193], v145 offset:16384
	ds_read_b128 v[194:197], v145 offset:17408
	s_add_i32 m0, s53, 0x2000
	s_add_u32 s54, s18, 0x100000
	v_lshl_add_u64 v[186:187], s[18:19], 0, v[130:131]
	s_addc_u32 s55, s19, 0
	s_add_i32 s53, s56, s26
	global_load_lds_dwordx4 v[186:187], off
	ds_read_b128 v[198:201], v145 offset:18432
	ds_read_b128 v[202:205], v145 offset:19456
	v_lshl_add_u64 v[188:189], s[54:55], 0, v[0:1]
	s_mov_b32 m0, s53
	v_lshl_add_u64 v[210:211], s[22:23], 0, v[132:133]
	global_load_lds_dwordx4 v[188:189], off
	ds_read_b128 v[206:209], v145 offset:20480
	ds_read_b128 v[228:231], v145 offset:21504
	v_lshl_add_u64 v[188:189], s[54:55], 0, v[130:131]
	s_add_i32 m0, s53, 0x2000
	s_nop 0
	global_load_lds_dwordx4 v[188:189], off
	ds_read_b128 v[232:235], v145 offset:22528
	ds_read_b128 v[236:239], v145 offset:23552
	v_lshl_add_u64 v[188:189], s[22:23], 0, v[134:135]
	s_mov_b32 m0, s31
	s_nop 0
	global_load_lds_dwordx4 v[188:189], off
	s_mov_b32 m0, s40
	s_nop 0
	global_load_lds_dwordx4 v[210:211], off
	s_cmp_eq_u32 s52, -2
	s_cbranch_scc1 .Lz0_2_1
	s_waitcnt vmcnt(8)
	s_waitcnt lgkmcnt(0)
	s_setprio 1
	s_barrier
	v_mfma_f32_16x16x32_bf16 v[62:65], v[146:149], v[190:193], v[62:65]
	v_mfma_f32_16x16x32_bf16 v[62:65], v[150:153], v[194:197], v[62:65]
	v_mfma_f32_16x16x32_bf16 v[46:49], v[150:153], v[202:205], v[46:49]
	v_mfma_f32_16x16x32_bf16 v[46:49], v[146:149], v[198:201], v[46:49]
	v_mfma_f32_16x16x32_bf16 v[30:33], v[146:149], v[206:209], v[30:33]
	v_mfma_f32_16x16x32_bf16 v[30:33], v[150:153], v[228:231], v[30:33]
	v_mfma_f32_16x16x32_bf16 v[14:17], v[150:153], v[236:239], v[14:17]
	v_mfma_f32_16x16x32_bf16 v[14:17], v[146:149], v[232:235], v[14:17]
	v_mfma_f32_16x16x32_bf16 v[6:9], v[154:157], v[232:235], v[6:9]
	v_mfma_f32_16x16x32_bf16 v[6:9], v[158:161], v[236:239], v[6:9]
	v_mfma_f32_16x16x32_bf16 v[22:25], v[158:161], v[228:231], v[22:25]
	v_mfma_f32_16x16x32_bf16 v[22:25], v[154:157], v[206:209], v[22:25]
	v_mfma_f32_16x16x32_bf16 v[38:41], v[154:157], v[198:201], v[38:41]
	v_mfma_f32_16x16x32_bf16 v[38:41], v[158:161], v[202:205], v[38:41]
	v_mfma_f32_16x16x32_bf16 v[54:57], v[158:161], v[194:197], v[54:57]
	v_mfma_f32_16x16x32_bf16 v[54:57], v[154:157], v[190:193], v[54:57]
	v_mfma_f32_16x16x32_bf16 v[58:61], v[162:165], v[190:193], v[58:61]
	v_mfma_f32_16x16x32_bf16 v[58:61], v[166:169], v[194:197], v[58:61]
	v_mfma_f32_16x16x32_bf16 v[42:45], v[166:169], v[202:205], v[42:45]
	v_mfma_f32_16x16x32_bf16 v[42:45], v[162:165], v[198:201], v[42:45]
	v_mfma_f32_16x16x32_bf16 v[26:29], v[162:165], v[206:209], v[26:29]
	v_mfma_f32_16x16x32_bf16 v[26:29], v[166:169], v[228:231], v[26:29]
	v_mfma_f32_16x16x32_bf16 v[10:13], v[166:169], v[236:239], v[10:13]
	v_mfma_f32_16x16x32_bf16 v[10:13], v[162:165], v[232:235], v[10:13]
	v_mfma_f32_16x16x32_bf16 v[2:5], v[170:173], v[232:235], v[2:5]
	v_mfma_f32_16x16x32_bf16 v[2:5], v[178:181], v[236:239], v[2:5]
	v_mfma_f32_16x16x32_bf16 v[18:21], v[178:181], v[228:231], v[18:21]
	v_mfma_f32_16x16x32_bf16 v[18:21], v[170:173], v[206:209], v[18:21]
	v_mfma_f32_16x16x32_bf16 v[34:37], v[170:173], v[198:201], v[34:37]
	v_mfma_f32_16x16x32_bf16 v[34:37], v[178:181], v[202:205], v[34:37]
	v_mfma_f32_16x16x32_bf16 v[50:53], v[178:181], v[194:197], v[50:53]
	v_mfma_f32_16x16x32_bf16 v[50:53], v[170:173], v[190:193], v[50:53]
	s_barrier
	s_setprio 0
.Lz0_2_1_ret:
	s_add_i32 s53, 0, 0x18000
	s_add_i32 s54, 0, 0x1c000
	v_add_u32_e32 v158, s53, v143
	v_add_u32_e32 v175, s54, v143
	ds_read_b128 v[146:149], v158
	ds_read_b128 v[150:153], v158 offset:1024
	ds_read_b128 v[154:157], v158 offset:2048
	ds_read_b128 v[158:161], v158 offset:3072
	ds_read_b128 v[162:165], v175
	ds_read_b128 v[166:169], v175 offset:1024
	ds_read_b128 v[170:173], v175 offset:2048
	ds_read_b128 v[178:181], v175 offset:3072
	s_add_u32 s22, s22, 0x100000
	s_addc_u32 s23, s23, 0
	s_mov_b32 m0, s41
	v_lshl_add_u64 v[226:227], s[22:23], 0, v[134:135]
	ds_read_b128 v[190:193], v145 offset:32768
	ds_read_b128 v[194:197], v145 offset:33792
	ds_read_b128 v[198:201], v145 offset:34816
	ds_read_b128 v[202:205], v145 offset:35840
	ds_read_b128 v[206:209], v145 offset:36864
	ds_read_b128 v[228:231], v145 offset:37888
	ds_read_b128 v[232:235], v145 offset:38912
	ds_read_b128 v[236:239], v145 offset:39936
	global_load_lds_dwordx4 v[226:227], off
	v_lshl_add_u64 v[226:227], s[22:23], 0, v[132:133]
	s_mov_b32 m0, s42
	s_nop 0
	global_load_lds_dwordx4 v[226:227], off
	s_waitcnt vmcnt(8)
	s_waitcnt lgkmcnt(0)
	s_setprio 1
	s_barrier
	v_mfma_f32_16x16x32_bf16 v[126:129], v[146:149], v[190:193], v[126:129]
	v_mfma_f32_16x16x32_bf16 v[126:129], v[150:153], v[194:197], v[126:129]
	v_mfma_f32_16x16x32_bf16 v[110:113], v[150:153], v[202:205], v[110:113]
	v_mfma_f32_16x16x32_bf16 v[110:113], v[146:149], v[198:201], v[110:113]
	v_mfma_f32_16x16x32_bf16 v[94:97], v[146:149], v[206:209], v[94:97]
	v_mfma_f32_16x16x32_bf16 v[94:97], v[150:153], v[228:231], v[94:97]
	v_mfma_f32_16x16x32_bf16 v[78:81], v[150:153], v[236:239], v[78:81]
	v_mfma_f32_16x16x32_bf16 v[78:81], v[146:149], v[232:235], v[78:81]
	v_mfma_f32_16x16x32_bf16 v[70:73], v[154:157], v[232:235], v[70:73]
	v_mfma_f32_16x16x32_bf16 v[70:73], v[158:161], v[236:239], v[70:73]
	v_mfma_f32_16x16x32_bf16 v[86:89], v[158:161], v[228:231], v[86:89]
	v_mfma_f32_16x16x32_bf16 v[86:89], v[154:157], v[206:209], v[86:89]
	v_mfma_f32_16x16x32_bf16 v[102:105], v[154:157], v[198:201], v[102:105]
	v_mfma_f32_16x16x32_bf16 v[102:105], v[158:161], v[202:205], v[102:105]
	v_mfma_f32_16x16x32_bf16 v[118:121], v[158:161], v[194:197], v[118:121]
	v_mfma_f32_16x16x32_bf16 v[118:121], v[154:157], v[190:193], v[118:121]
	v_mfma_f32_16x16x32_bf16 v[122:125], v[162:165], v[190:193], v[122:125]
	v_mfma_f32_16x16x32_bf16 v[122:125], v[166:169], v[194:197], v[122:125]
	v_mfma_f32_16x16x32_bf16 v[106:109], v[166:169], v[202:205], v[106:109]
	v_mfma_f32_16x16x32_bf16 v[106:109], v[162:165], v[198:201], v[106:109]
	v_mfma_f32_16x16x32_bf16 v[90:93], v[162:165], v[206:209], v[90:93]
	v_mfma_f32_16x16x32_bf16 v[90:93], v[166:169], v[228:231], v[90:93]
	v_mfma_f32_16x16x32_bf16 v[74:77], v[166:169], v[236:239], v[74:77]
	v_mfma_f32_16x16x32_bf16 v[74:77], v[162:165], v[232:235], v[74:77]
	v_mfma_f32_16x16x32_bf16 v[66:69], v[170:173], v[232:235], v[66:69]
	v_mfma_f32_16x16x32_bf16 v[66:69], v[178:181], v[236:239], v[66:69]
	v_mfma_f32_16x16x32_bf16 v[82:85], v[178:181], v[228:231], v[82:85]
	v_mfma_f32_16x16x32_bf16 v[82:85], v[170:173], v[206:209], v[82:85]
	v_mfma_f32_16x16x32_bf16 v[98:101], v[170:173], v[198:201], v[98:101]
	v_mfma_f32_16x16x32_bf16 v[98:101], v[178:181], v[202:205], v[98:101]
	v_mfma_f32_16x16x32_bf16 v[114:117], v[178:181], v[194:197], v[114:117]
	v_mfma_f32_16x16x32_bf16 v[114:117], v[170:173], v[190:193], v[114:117]
	s_barrier
	s_setprio 0
	s_add_i32 s22, s53, s26
	v_lshl_add_u64 v[140:141], v[140:141], 0, s[34:35]
	s_mov_b32 m0, s22
	s_nop 0
	global_load_lds_dwordx4 v[140:141], off
	ds_read_b128 v[190:193], v145 offset:49152
	ds_read_b128 v[194:197], v145 offset:50176
	s_add_i32 m0, s22, 0x2000
	s_add_u32 s18, s18, 0x100080
	v_lshl_add_u64 v[140:141], v[186:187], 0, s[34:35]
	s_addc_u32 s19, s19, 0
	s_add_i32 s22, s54, s26
	global_load_lds_dwordx4 v[140:141], off
	ds_read_b128 v[198:201], v145 offset:51200
	ds_read_b128 v[202:205], v145 offset:52224
	v_lshl_add_u64 v[140:141], s[18:19], 0, v[0:1]
	s_mov_b32 m0, s22
	s_nop 0
	global_load_lds_dwordx4 v[140:141], off
	ds_read_b128 v[206:209], v145 offset:53248
	ds_read_b128 v[228:231], v145 offset:54272
	v_lshl_add_u64 v[140:141], s[18:19], 0, v[130:131]
	s_add_i32 m0, s22, 0x2000
	s_nop 0
	global_load_lds_dwordx4 v[140:141], off
	ds_read_b128 v[232:235], v145 offset:55296
	ds_read_b128 v[236:239], v145 offset:56320
	v_lshl_add_u64 v[140:141], v[188:189], 0, s[34:35]
	s_mov_b32 m0, s43
	s_nop 0
	global_load_lds_dwordx4 v[140:141], off
	v_lshl_add_u64 v[140:141], v[210:211], 0, s[34:35]
	s_mov_b32 m0, s44
	s_nop 0
	global_load_lds_dwordx4 v[140:141], off
	s_waitcnt vmcnt(8)
	s_waitcnt lgkmcnt(0)
	s_setprio 1
	s_barrier
	v_mfma_f32_16x16x32_bf16 v[62:65], v[146:149], v[190:193], v[62:65]
	v_mfma_f32_16x16x32_bf16 v[62:65], v[150:153], v[194:197], v[62:65]
	v_mfma_f32_16x16x32_bf16 v[46:49], v[150:153], v[202:205], v[46:49]
	v_mfma_f32_16x16x32_bf16 v[46:49], v[146:149], v[198:201], v[46:49]
	v_mfma_f32_16x16x32_bf16 v[30:33], v[146:149], v[206:209], v[30:33]
	v_mfma_f32_16x16x32_bf16 v[30:33], v[150:153], v[228:231], v[30:33]
	v_mfma_f32_16x16x32_bf16 v[14:17], v[150:153], v[236:239], v[14:17]
	v_mfma_f32_16x16x32_bf16 v[14:17], v[146:149], v[232:235], v[14:17]
	v_mfma_f32_16x16x32_bf16 v[6:9], v[154:157], v[232:235], v[6:9]
	v_mfma_f32_16x16x32_bf16 v[6:9], v[158:161], v[236:239], v[6:9]
	v_mfma_f32_16x16x32_bf16 v[22:25], v[158:161], v[228:231], v[22:25]
	v_mfma_f32_16x16x32_bf16 v[22:25], v[154:157], v[206:209], v[22:25]
	v_mfma_f32_16x16x32_bf16 v[38:41], v[154:157], v[198:201], v[38:41]
	v_mfma_f32_16x16x32_bf16 v[38:41], v[158:161], v[202:205], v[38:41]
	v_mfma_f32_16x16x32_bf16 v[54:57], v[158:161], v[194:197], v[54:57]
	v_mfma_f32_16x16x32_bf16 v[54:57], v[154:157], v[190:193], v[54:57]
	v_mfma_f32_16x16x32_bf16 v[58:61], v[162:165], v[190:193], v[58:61]
	v_mfma_f32_16x16x32_bf16 v[58:61], v[166:169], v[194:197], v[58:61]
	v_mfma_f32_16x16x32_bf16 v[42:45], v[166:169], v[202:205], v[42:45]
	v_mfma_f32_16x16x32_bf16 v[42:45], v[162:165], v[198:201], v[42:45]
	v_mfma_f32_16x16x32_bf16 v[26:29], v[162:165], v[206:209], v[26:29]
	v_mfma_f32_16x16x32_bf16 v[26:29], v[166:169], v[228:231], v[26:29]
	v_mfma_f32_16x16x32_bf16 v[10:13], v[166:169], v[236:239], v[10:13]
	v_mfma_f32_16x16x32_bf16 v[10:13], v[162:165], v[232:235], v[10:13]
	v_mfma_f32_16x16x32_bf16 v[2:5], v[170:173], v[232:235], v[2:5]
	v_mfma_f32_16x16x32_bf16 v[2:5], v[178:181], v[236:239], v[2:5]
	v_mfma_f32_16x16x32_bf16 v[18:21], v[178:181], v[228:231], v[18:21]
	v_mfma_f32_16x16x32_bf16 v[18:21], v[170:173], v[206:209], v[18:21]
	v_mfma_f32_16x16x32_bf16 v[34:37], v[170:173], v[198:201], v[34:37]
	v_mfma_f32_16x16x32_bf16 v[34:37], v[178:181], v[202:205], v[34:37]
	v_mfma_f32_16x16x32_bf16 v[50:53], v[178:181], v[194:197], v[50:53]
	v_mfma_f32_16x16x32_bf16 v[50:53], v[170:173], v[190:193], v[50:53]
	s_barrier
	s_setprio 0
	s_add_i32 s52, s52, 2
	s_add_u32 s16, s16, 0x100
	s_addc_u32 s17, s17, 0
	s_add_u32 s50, s50, 0x100
	s_addc_u32 s51, s51, 0
	s_cmp_gt_u32 s52, 61
	s_cbranch_scc0 .LBB0_721
	s_and_b64 vcc, exec, s[2:3]
	s_cbranch_vccz .LBB0_724
	s_barrier

.Lz0_3_0_ret:
	s_add_i32 s14, s49, s26
	v_lshl_add_u64 v[140:141], s[18:19], 0, v[0:1]
	s_mov_b32 m0, s14
	s_nop 0
	global_load_lds_dwordx4 v[140:141], off
	ds_read_b128 v[190:193], v145 offset:16384
	ds_read_b128 v[194:197], v145 offset:17408
	s_add_i32 m0, s14, 0x2000
	s_add_u32 s14, s18, 0x2b0000
	v_lshl_add_u64 v[186:187], s[18:19], 0, v[130:131]
	s_addc_u32 s15, s19, 0
	s_add_i32 s49, s50, s26
	global_load_lds_dwordx4 v[186:187], off
	ds_read_b128 v[198:201], v145 offset:18432
	ds_read_b128 v[202:205], v145 offset:19456
	v_lshl_add_u64 v[188:189], s[14:15], 0, v[0:1]
	s_mov_b32 m0, s49
	v_lshl_add_u64 v[210:211], s[22:23], 0, v[132:133]
	global_load_lds_dwordx4 v[188:189], off
	ds_read_b128 v[206:209], v145 offset:20480
	ds_read_b128 v[228:231], v145 offset:21504
	v_lshl_add_u64 v[188:189], s[14:15], 0, v[130:131]
	s_add_i32 m0, s49, 0x2000
	s_nop 0
	global_load_lds_dwordx4 v[188:189], off
	ds_read_b128 v[232:235], v145 offset:22528
	ds_read_b128 v[236:239], v145 offset:23552
	v_lshl_add_u64 v[188:189], s[22:23], 0, v[134:135]
	s_mov_b32 m0, s31
	s_nop 0
	global_load_lds_dwordx4 v[188:189], off
	s_mov_b32 m0, s36
	s_nop 0
	global_load_lds_dwordx4 v[210:211], off
	s_cmp_eq_u32 s48, -2
	s_cbranch_scc1 .Lz0_3_1
	s_waitcnt vmcnt(8)
	s_waitcnt lgkmcnt(0)
	s_setprio 1
	s_barrier
	v_mfma_f32_16x16x32_bf16 v[62:65], v[146:149], v[190:193], v[62:65]
	v_mfma_f32_16x16x32_bf16 v[62:65], v[150:153], v[194:197], v[62:65]
	v_mfma_f32_16x16x32_bf16 v[54:57], v[150:153], v[202:205], v[54:57]
	v_mfma_f32_16x16x32_bf16 v[54:57], v[146:149], v[198:201], v[54:57]
	v_mfma_f32_16x16x32_bf16 v[38:41], v[146:149], v[206:209], v[38:41]
	v_mfma_f32_16x16x32_bf16 v[38:41], v[150:153], v[228:231], v[38:41]
	v_mfma_f32_16x16x32_bf16 v[22:25], v[150:153], v[236:239], v[22:25]
	v_mfma_f32_16x16x32_bf16 v[22:25], v[146:149], v[232:235], v[22:25]
	v_mfma_f32_16x16x32_bf16 v[14:17], v[154:157], v[232:235], v[14:17]
	v_mfma_f32_16x16x32_bf16 v[14:17], v[158:161], v[236:239], v[14:17]
	v_mfma_f32_16x16x32_bf16 v[30:33], v[158:161], v[228:231], v[30:33]
	v_mfma_f32_16x16x32_bf16 v[30:33], v[154:157], v[206:209], v[30:33]
	v_mfma_f32_16x16x32_bf16 v[46:49], v[154:157], v[198:201], v[46:49]
	v_mfma_f32_16x16x32_bf16 v[46:49], v[158:161], v[202:205], v[46:49]
	v_mfma_f32_16x16x32_bf16 v[58:61], v[158:161], v[194:197], v[58:61]
	v_mfma_f32_16x16x32_bf16 v[58:61], v[154:157], v[190:193], v[58:61]
	v_mfma_f32_16x16x32_bf16 v[50:53], v[162:165], v[190:193], v[50:53]
	v_mfma_f32_16x16x32_bf16 v[50:53], v[166:169], v[194:197], v[50:53]
	v_mfma_f32_16x16x32_bf16 v[34:37], v[166:169], v[202:205], v[34:37]
	v_mfma_f32_16x16x32_bf16 v[34:37], v[162:165], v[198:201], v[34:37]
	v_mfma_f32_16x16x32_bf16 v[18:21], v[162:165], v[206:209], v[18:21]
	v_mfma_f32_16x16x32_bf16 v[18:21], v[166:169], v[228:231], v[18:21]
	v_mfma_f32_16x16x32_bf16 v[6:9], v[166:169], v[236:239], v[6:9]
	v_mfma_f32_16x16x32_bf16 v[6:9], v[162:165], v[232:235], v[6:9]
	v_mfma_f32_16x16x32_bf16 v[2:5], v[170:173], v[232:235], v[2:5]
	v_mfma_f32_16x16x32_bf16 v[2:5], v[178:181], v[236:239], v[2:5]
	v_mfma_f32_16x16x32_bf16 v[10:13], v[178:181], v[228:231], v[10:13]
	v_mfma_f32_16x16x32_bf16 v[10:13], v[170:173], v[206:209], v[10:13]
	v_mfma_f32_16x16x32_bf16 v[26:29], v[170:173], v[198:201], v[26:29]
	v_mfma_f32_16x16x32_bf16 v[26:29], v[178:181], v[202:205], v[26:29]
	v_mfma_f32_16x16x32_bf16 v[42:45], v[178:181], v[194:197], v[42:45]
	v_mfma_f32_16x16x32_bf16 v[42:45], v[170:173], v[190:193], v[42:45]
	s_barrier
	s_setprio 0
.Lz0_3_1_ret:
	s_add_i32 s49, 0, 0x18000
	s_add_i32 s50, 0, 0x1c000
	v_add_u32_e32 v158, s49, v143
	v_add_u32_e32 v175, s50, v143
	ds_read_b128 v[146:149], v158
	ds_read_b128 v[150:153], v158 offset:1024
	ds_read_b128 v[154:157], v158 offset:2048
	ds_read_b128 v[158:161], v158 offset:3072
	ds_read_b128 v[162:165], v175
	ds_read_b128 v[166:169], v175 offset:1024
	ds_read_b128 v[170:173], v175 offset:2048
	ds_read_b128 v[178:181], v175 offset:3072
	s_add_u32 s14, s22, 0x2b0000
	s_addc_u32 s15, s23, 0
	s_mov_b32 m0, s37
	v_lshl_add_u64 v[226:227], s[14:15], 0, v[134:135]
	ds_read_b128 v[190:193], v145 offset:32768
	ds_read_b128 v[194:197], v145 offset:33792
	ds_read_b128 v[198:201], v145 offset:34816
	ds_read_b128 v[202:205], v145 offset:35840
	ds_read_b128 v[206:209], v145 offset:36864
	ds_read_b128 v[228:231], v145 offset:37888
	ds_read_b128 v[232:235], v145 offset:38912
	ds_read_b128 v[236:239], v145 offset:39936
	global_load_lds_dwordx4 v[226:227], off
	v_lshl_add_u64 v[226:227], s[14:15], 0, v[132:133]
	s_mov_b32 m0, s38
	s_nop 0
	global_load_lds_dwordx4 v[226:227], off
	s_waitcnt vmcnt(8)
	s_waitcnt lgkmcnt(0)
	s_setprio 1
	s_barrier
	v_mfma_f32_16x16x32_bf16 v[126:129], v[146:149], v[190:193], v[126:129]
	v_mfma_f32_16x16x32_bf16 v[126:129], v[150:153], v[194:197], v[126:129]
	v_mfma_f32_16x16x32_bf16 v[118:121], v[150:153], v[202:205], v[118:121]
	v_mfma_f32_16x16x32_bf16 v[118:121], v[146:149], v[198:201], v[118:121]
	v_mfma_f32_16x16x32_bf16 v[102:105], v[146:149], v[206:209], v[102:105]
	v_mfma_f32_16x16x32_bf16 v[102:105], v[150:153], v[228:231], v[102:105]
	v_mfma_f32_16x16x32_bf16 v[86:89], v[150:153], v[236:239], v[86:89]
	v_mfma_f32_16x16x32_bf16 v[86:89], v[146:149], v[232:235], v[86:89]
	v_mfma_f32_16x16x32_bf16 v[78:81], v[154:157], v[232:235], v[78:81]
	v_mfma_f32_16x16x32_bf16 v[78:81], v[158:161], v[236:239], v[78:81]
	v_mfma_f32_16x16x32_bf16 v[94:97], v[158:161], v[228:231], v[94:97]
	v_mfma_f32_16x16x32_bf16 v[94:97], v[154:157], v[206:209], v[94:97]
	v_mfma_f32_16x16x32_bf16 v[110:113], v[154:157], v[198:201], v[110:113]
	v_mfma_f32_16x16x32_bf16 v[110:113], v[158:161], v[202:205], v[110:113]
	v_mfma_f32_16x16x32_bf16 v[122:125], v[158:161], v[194:197], v[122:125]
	v_mfma_f32_16x16x32_bf16 v[122:125], v[154:157], v[190:193], v[122:125]
	v_mfma_f32_16x16x32_bf16 v[114:117], v[162:165], v[190:193], v[114:117]
	v_mfma_f32_16x16x32_bf16 v[114:117], v[166:169], v[194:197], v[114:117]
	v_mfma_f32_16x16x32_bf16 v[98:101], v[166:169], v[202:205], v[98:101]
	v_mfma_f32_16x16x32_bf16 v[98:101], v[162:165], v[198:201], v[98:101]
	v_mfma_f32_16x16x32_bf16 v[82:85], v[162:165], v[206:209], v[82:85]
	v_mfma_f32_16x16x32_bf16 v[82:85], v[166:169], v[228:231], v[82:85]
	v_mfma_f32_16x16x32_bf16 v[70:73], v[166:169], v[236:239], v[70:73]
	v_mfma_f32_16x16x32_bf16 v[70:73], v[162:165], v[232:235], v[70:73]
	v_mfma_f32_16x16x32_bf16 v[66:69], v[170:173], v[232:235], v[66:69]
	v_mfma_f32_16x16x32_bf16 v[66:69], v[178:181], v[236:239], v[66:69]
	v_mfma_f32_16x16x32_bf16 v[74:77], v[178:181], v[228:231], v[74:77]
	v_mfma_f32_16x16x32_bf16 v[74:77], v[170:173], v[206:209], v[74:77]
	v_mfma_f32_16x16x32_bf16 v[90:93], v[170:173], v[198:201], v[90:93]
	v_mfma_f32_16x16x32_bf16 v[90:93], v[178:181], v[202:205], v[90:93]
	v_mfma_f32_16x16x32_bf16 v[106:109], v[178:181], v[194:197], v[106:109]
	v_mfma_f32_16x16x32_bf16 v[106:109], v[170:173], v[190:193], v[106:109]
	s_barrier
	s_setprio 0
	s_add_i32 s14, s49, s26
	v_lshl_add_u64 v[140:141], v[140:141], 0, s[34:35]
	s_mov_b32 m0, s14
	s_nop 0
	global_load_lds_dwordx4 v[140:141], off
	ds_read_b128 v[190:193], v145 offset:49152
	ds_read_b128 v[194:197], v145 offset:50176
	s_add_i32 m0, s14, 0x2000
	s_add_u32 s14, s18, 0x2b0080
	v_lshl_add_u64 v[140:141], v[186:187], 0, s[34:35]
	s_addc_u32 s15, s19, 0
	s_add_i32 s18, s50, s26
	global_load_lds_dwordx4 v[140:141], off
	ds_read_b128 v[198:201], v145 offset:51200
	ds_read_b128 v[202:205], v145 offset:52224
	v_lshl_add_u64 v[140:141], s[14:15], 0, v[0:1]
	s_mov_b32 m0, s18
	s_nop 0
	global_load_lds_dwordx4 v[140:141], off
	ds_read_b128 v[206:209], v145 offset:53248
	ds_read_b128 v[228:231], v145 offset:54272
	v_lshl_add_u64 v[140:141], s[14:15], 0, v[130:131]
	s_add_i32 m0, s18, 0x2000
	s_nop 0
	global_load_lds_dwordx4 v[140:141], off
	ds_read_b128 v[232:235], v145 offset:55296
	ds_read_b128 v[236:239], v145 offset:56320
	v_lshl_add_u64 v[140:141], v[188:189], 0, s[34:35]
	s_mov_b32 m0, s39
	s_nop 0
	global_load_lds_dwordx4 v[140:141], off
	v_lshl_add_u64 v[140:141], v[210:211], 0, s[34:35]
	s_mov_b32 m0, s40
	s_nop 0
	global_load_lds_dwordx4 v[140:141], off
	s_waitcnt vmcnt(8)
	s_waitcnt lgkmcnt(0)
	s_setprio 1
	s_barrier
	v_mfma_f32_16x16x32_bf16 v[62:65], v[146:149], v[190:193], v[62:65]
	v_mfma_f32_16x16x32_bf16 v[62:65], v[150:153], v[194:197], v[62:65]
	v_mfma_f32_16x16x32_bf16 v[54:57], v[150:153], v[202:205], v[54:57]
	v_mfma_f32_16x16x32_bf16 v[54:57], v[146:149], v[198:201], v[54:57]
	v_mfma_f32_16x16x32_bf16 v[38:41], v[146:149], v[206:209], v[38:41]
	v_mfma_f32_16x16x32_bf16 v[38:41], v[150:153], v[228:231], v[38:41]
	v_mfma_f32_16x16x32_bf16 v[22:25], v[150:153], v[236:239], v[22:25]
	v_mfma_f32_16x16x32_bf16 v[22:25], v[146:149], v[232:235], v[22:25]
	v_mfma_f32_16x16x32_bf16 v[14:17], v[154:157], v[232:235], v[14:17]
	v_mfma_f32_16x16x32_bf16 v[14:17], v[158:161], v[236:239], v[14:17]
	v_mfma_f32_16x16x32_bf16 v[30:33], v[158:161], v[228:231], v[30:33]
	v_mfma_f32_16x16x32_bf16 v[30:33], v[154:157], v[206:209], v[30:33]
	v_mfma_f32_16x16x32_bf16 v[46:49], v[154:157], v[198:201], v[46:49]
	v_mfma_f32_16x16x32_bf16 v[46:49], v[158:161], v[202:205], v[46:49]
	v_mfma_f32_16x16x32_bf16 v[58:61], v[158:161], v[194:197], v[58:61]
	v_mfma_f32_16x16x32_bf16 v[58:61], v[154:157], v[190:193], v[58:61]
	v_mfma_f32_16x16x32_bf16 v[50:53], v[162:165], v[190:193], v[50:53]
	v_mfma_f32_16x16x32_bf16 v[50:53], v[166:169], v[194:197], v[50:53]
	v_mfma_f32_16x16x32_bf16 v[34:37], v[166:169], v[202:205], v[34:37]
	v_mfma_f32_16x16x32_bf16 v[34:37], v[162:165], v[198:201], v[34:37]
	v_mfma_f32_16x16x32_bf16 v[18:21], v[162:165], v[206:209], v[18:21]
	v_mfma_f32_16x16x32_bf16 v[18:21], v[166:169], v[228:231], v[18:21]
	v_mfma_f32_16x16x32_bf16 v[6:9], v[166:169], v[236:239], v[6:9]
	v_mfma_f32_16x16x32_bf16 v[6:9], v[162:165], v[232:235], v[6:9]
	v_mfma_f32_16x16x32_bf16 v[2:5], v[170:173], v[232:235], v[2:5]
	v_mfma_f32_16x16x32_bf16 v[2:5], v[178:181], v[236:239], v[2:5]
	v_mfma_f32_16x16x32_bf16 v[10:13], v[178:181], v[228:231], v[10:13]
	v_mfma_f32_16x16x32_bf16 v[10:13], v[170:173], v[206:209], v[10:13]
	v_mfma_f32_16x16x32_bf16 v[26:29], v[170:173], v[198:201], v[26:29]
	v_mfma_f32_16x16x32_bf16 v[26:29], v[178:181], v[202:205], v[26:29]
	v_mfma_f32_16x16x32_bf16 v[42:45], v[178:181], v[194:197], v[42:45]
	v_mfma_f32_16x16x32_bf16 v[42:45], v[170:173], v[190:193], v[42:45]
	s_barrier
	s_setprio 0
	s_add_i32 s48, s48, 2
	s_add_u32 s46, s46, 0x100
	s_addc_u32 s47, s47, 0
	s_cmpk_gt_u32 s48, 0xa9
	s_mov_b64 s[14:15], s[16:17]
	s_cbranch_scc0 .LBB0_805
	s_and_b64 vcc, exec, s[6:7]
	s_cbranch_vccz .LBB0_808
	s_barrier
